# accumulator zeroing with v_mov_b64, sample attention items spread over waves 0-1 of every CU, 14 unneeded s_nop removed in attention far path
# speedup vs baseline: 1.0049x; 1.0045x over previous
; template <class Epi, class Sched, bool ALIGN_EPI = false, bool SP2 = false>
; __device__ __forceinline__ void gemm_phase(PG8_LAS unsigned char* lds, const Gemm g, const Sched& S, const Epi& E) {
;     ...
;         const char* nA = has_next ? (const char*)g.A + (size_t)nxt.pm * tstepA + (size_t)nxt.kz * kzb : cA; const char* nB = has_next ? (const char*)g.Bt + (size_t)nxt.pn * tstepB + (size_t)nxt.kz * kzb : cB;
;     ...
;         for (int a = 0; a < 2; ++a)
; #pragma unroll
;             for (int b = 0; b < 2; ++b)
; #pragma unroll
;                 for (int m = 0; m < 4; ++m)
; #pragma unroll
;                     for (int n = 0; n < 2; ++n) acc[a][b][m][n] = (f32x4){0.f, 0.f, 0.f, 0.f};
.LBB0_310:
	s_ashr_i32 s61, s60, 31
	s_lshl_b64 s[62:63], s[60:61], 20
	v_readlane_b32 s64, v240, 26
	v_readlane_b32 s65, v240, 27
	s_add_u32 s62, s64, s62
	s_addc_u32 s63, s65, s63
	s_and_b64 s[64:65], s[4:5], exec
	s_cselect_b32 s20, s63, s7
	s_cselect_b32 s33, s62, s6
	s_ashr_i32 s55, s54, 31
	s_lshl_b64 s[64:65], s[54:55], 20
	v_readlane_b32 s76, v240, 3
	v_readlane_b32 s77, v240, 4
	s_add_u32 s64, s76, s64
	s_addc_u32 s65, s77, s65
	s_and_b64 s[70:71], s[4:5], exec
	s_cselect_b32 s55, s65, s69
	s_cselect_b32 s61, s64, s68
	s_add_u32 s6, s6, 0x80080
	s_addc_u32 s7, s7, 0
	v_readlane_b32 s78, v240, 5
	s_add_u32 s76, s68, 0x100
	v_mov_b64_e32 v[0:1], 0
	s_addc_u32 s77, s69, 0
	s_mov_b32 s78, -2
	v_mov_b64_e32 v[2:3], 0
	v_mov_b64_e32 v[4:5], 0
	v_mov_b64_e32 v[6:7], 0
	v_mov_b64_e32 v[16:17], 0
	v_mov_b64_e32 v[18:19], 0
	v_mov_b64_e32 v[20:21], 0
	v_mov_b64_e32 v[22:23], 0
	v_mov_b64_e32 v[32:33], 0
	v_mov_b64_e32 v[34:35], 0
	v_mov_b64_e32 v[36:37], 0
	v_mov_b64_e32 v[38:39], 0
	v_mov_b64_e32 v[48:49], 0
	v_mov_b64_e32 v[50:51], 0
	v_mov_b64_e32 v[52:53], 0
	v_mov_b64_e32 v[54:55], 0
	v_mov_b64_e32 v[8:9], 0
	v_mov_b64_e32 v[10:11], 0
	v_mov_b64_e32 v[12:13], 0
	v_mov_b64_e32 v[14:15], 0
	v_mov_b64_e32 v[24:25], 0
	v_mov_b64_e32 v[26:27], 0
	v_mov_b64_e32 v[28:29], 0
	v_mov_b64_e32 v[30:31], 0
	v_mov_b64_e32 v[40:41], 0
	v_mov_b64_e32 v[42:43], 0
	v_mov_b64_e32 v[44:45], 0
	v_mov_b64_e32 v[46:47], 0
	v_mov_b64_e32 v[56:57], 0
	v_mov_b64_e32 v[58:59], 0
	v_mov_b64_e32 v[60:61], 0
	v_mov_b64_e32 v[62:63], 0
	v_mov_b64_e32 v[64:65], 0
	v_mov_b64_e32 v[66:67], 0
	v_mov_b64_e32 v[68:69], 0
	v_mov_b64_e32 v[70:71], 0
	v_mov_b64_e32 v[80:81], 0
	v_mov_b64_e32 v[82:83], 0
	v_mov_b64_e32 v[84:85], 0
	v_mov_b64_e32 v[86:87], 0
	v_mov_b64_e32 v[96:97], 0
	v_mov_b64_e32 v[98:99], 0
	v_mov_b64_e32 v[100:101], 0
	v_mov_b64_e32 v[102:103], 0
	v_mov_b64_e32 v[112:113], 0
	v_mov_b64_e32 v[114:115], 0
	v_mov_b64_e32 v[116:117], 0
	v_mov_b64_e32 v[118:119], 0
	v_mov_b64_e32 v[72:73], 0
	v_mov_b64_e32 v[74:75], 0
	v_mov_b64_e32 v[76:77], 0
	v_mov_b64_e32 v[78:79], 0
	v_mov_b64_e32 v[88:89], 0
	v_mov_b64_e32 v[90:91], 0
	v_mov_b64_e32 v[92:93], 0
	v_mov_b64_e32 v[94:95], 0
	v_mov_b64_e32 v[104:105], 0
	v_mov_b64_e32 v[106:107], 0
	v_mov_b64_e32 v[108:109], 0
	v_mov_b64_e32 v[110:111], 0
	v_mov_b64_e32 v[120:121], 0
	v_mov_b64_e32 v[122:123], 0
	v_mov_b64_e32 v[124:125], 0
	v_mov_b64_e32 v[126:127], 0
	v_readlane_b32 s79, v240, 6

; template <class Epi, class Sched, bool ALIGN_EPI = false, bool SP2 = false>
; __device__ __forceinline__ void gemm_phase(PG8_LAS unsigned char* lds, const Gemm g, const Sched& S, const Epi& E) {
;     ...
;         const char* nA = has_next ? (const char*)g.A + (size_t)nxt.pm * tstepA + (size_t)nxt.kz * kzb : cA; const char* nB = has_next ? (const char*)g.Bt + (size_t)nxt.pn * tstepB + (size_t)nxt.kz * kzb : cB;
;     ...
;         for (int a = 0; a < 2; ++a)
; #pragma unroll
;             for (int b = 0; b < 2; ++b)
; #pragma unroll
;                 for (int m = 0; m < 4; ++m)
; #pragma unroll
;                     for (int n = 0; n < 2; ++n) acc[a][b][m][n] = (f32x4){0.f, 0.f, 0.f, 0.f};
.LBB0_496:
	s_ashr_i32 s43, s42, 31
	s_lshl_b64 s[28:29], s[42:43], 20
	s_add_u32 s46, s64, s28
	s_addc_u32 s47, s65, s29
	s_and_b64 s[28:29], s[4:5], exec
	s_cselect_b32 s7, s47, s55
	s_cselect_b32 s28, s46, s54
	s_ashr_i32 s41, s40, 31
	s_lshl_b64 s[30:31], s[40:41], 20
	v_readlane_b32 s48, v240, 26
	v_readlane_b32 s49, v240, 27
	s_add_u32 s48, s48, s30
	s_addc_u32 s49, s49, s31
	s_and_b64 s[30:31], s[4:5], exec
	s_cselect_b32 s29, s49, s61
	s_cselect_b32 s30, s48, s60
	s_add_u32 s54, s54, 0x80080
	s_addc_u32 s55, s55, 0
	s_add_u32 s31, s60, 0x100
	v_mov_b64_e32 v[0:1], 0
	s_addc_u32 s33, s61, 0
	s_mov_b32 s34, -2
	v_mov_b64_e32 v[2:3], 0
	v_mov_b64_e32 v[4:5], 0
	v_mov_b64_e32 v[6:7], 0
	v_mov_b64_e32 v[16:17], 0
	v_mov_b64_e32 v[18:19], 0
	v_mov_b64_e32 v[20:21], 0
	v_mov_b64_e32 v[22:23], 0
	v_mov_b64_e32 v[32:33], 0
	v_mov_b64_e32 v[34:35], 0
	v_mov_b64_e32 v[36:37], 0
	v_mov_b64_e32 v[38:39], 0
	v_mov_b64_e32 v[48:49], 0
	v_mov_b64_e32 v[50:51], 0
	v_mov_b64_e32 v[52:53], 0
	v_mov_b64_e32 v[54:55], 0
	v_mov_b64_e32 v[8:9], 0
	v_mov_b64_e32 v[10:11], 0
	v_mov_b64_e32 v[12:13], 0
	v_mov_b64_e32 v[14:15], 0
	v_mov_b64_e32 v[24:25], 0
	v_mov_b64_e32 v[26:27], 0
	v_mov_b64_e32 v[28:29], 0
	v_mov_b64_e32 v[30:31], 0
	v_mov_b64_e32 v[40:41], 0
	v_mov_b64_e32 v[42:43], 0
	v_mov_b64_e32 v[44:45], 0
	v_mov_b64_e32 v[46:47], 0
	v_mov_b64_e32 v[56:57], 0
	v_mov_b64_e32 v[58:59], 0
	v_mov_b64_e32 v[60:61], 0
	v_mov_b64_e32 v[62:63], 0
	v_mov_b64_e32 v[64:65], 0
	v_mov_b64_e32 v[66:67], 0
	v_mov_b64_e32 v[68:69], 0
	v_mov_b64_e32 v[70:71], 0
	v_mov_b64_e32 v[80:81], 0
	v_mov_b64_e32 v[82:83], 0
	v_mov_b64_e32 v[84:85], 0
	v_mov_b64_e32 v[86:87], 0
	v_mov_b64_e32 v[96:97], 0
	v_mov_b64_e32 v[98:99], 0
	v_mov_b64_e32 v[100:101], 0
	v_mov_b64_e32 v[102:103], 0
	v_mov_b64_e32 v[112:113], 0
	v_mov_b64_e32 v[114:115], 0
	v_mov_b64_e32 v[116:117], 0
	v_mov_b64_e32 v[118:119], 0
	v_mov_b64_e32 v[72:73], 0
	v_mov_b64_e32 v[74:75], 0
	v_mov_b64_e32 v[76:77], 0
	v_mov_b64_e32 v[78:79], 0
	v_mov_b64_e32 v[88:89], 0
	v_mov_b64_e32 v[90:91], 0
	v_mov_b64_e32 v[92:93], 0
	v_mov_b64_e32 v[94:95], 0
	v_mov_b64_e32 v[104:105], 0
	v_mov_b64_e32 v[106:107], 0
	v_mov_b64_e32 v[108:109], 0
	v_mov_b64_e32 v[110:111], 0
	v_mov_b64_e32 v[120:121], 0
	v_mov_b64_e32 v[122:123], 0
	v_mov_b64_e32 v[124:125], 0
	v_mov_b64_e32 v[126:127], 0

; #define LAS __attribute__((address_space(3)))
; __global__ void __launch_bounds__(NTHR, 2) fwd_megakernel(Args args) {
;     ...
;         constexpr int NQC = NB * NH * (SEQ / 64), NITEM = NQC + DECB * NH;
;         LAS unsigned char* ring = lds + 16384 + wave * 16384;
;         int rnd = 0;
;         for (int it = gw; it < NITEM; it += NGW, ++rnd) {
.LBB0_686:
	s_add_i32 s30, s30, s2
	s_add_i32 s29, s29, 1
	s_cmp_eq_u32 s29, 4
	s_cbranch_scc0 .Lattn_latch_std
	s_cmp_eq_u32 s2, 0x800
	s_cbranch_scc0 .Lattn_latch_std
	s_add_i32 s0, s30, 0xffffe000
	s_and_b32 s1, s0, 7
	s_cmp_gt_u32 s1, 1
	s_cbranch_scc1 .LBB0_658
	s_lshr_b32 s0, s0, 3
	s_lshl_b32 s0, s0, 1
	s_add_i32 s0, s0, s1
	s_add_i32 s30, s0, 0x2000
	s_branch .LBB0_687
.Lattn_latch_std:
	s_cmpk_gt_i32 s30, 0x21ff
	s_cbranch_scc1 .LBB0_658

.LBB0_728:
	s_andn2_b64 vcc, exec, s[52:53]
	s_cbranch_vccnz .LBB0_730
	v_sub_f32_e32 v113, v65, v191
	v_fma_f32 v82, v82, v224, v113
	v_exp_f32_e32 v98, v82
	v_fma_f32 v82, v83, v224, v113
	v_exp_f32_e32 v99, v82
	v_fma_f32 v82, v84, v224, v113
	v_exp_f32_e32 v100, v82
	v_fma_f32 v82, v85, v224, v113
	v_exp_f32_e32 v101, v82
	v_fma_f32 v82, v86, v224, v113
	v_exp_f32_e32 v102, v82
	v_fma_f32 v82, v87, v224, v113
	v_exp_f32_e32 v103, v82
	v_fma_f32 v82, v88, v224, v113
	v_exp_f32_e32 v104, v82
	v_fma_f32 v82, v89, v224, v113
	v_exp_f32_e32 v105, v82
	v_fma_f32 v82, v90, v224, v113
	v_exp_f32_e32 v106, v82
	v_fma_f32 v82, v91, v224, v113
	v_exp_f32_e32 v107, v82
	v_fma_f32 v82, v92, v224, v113
	v_exp_f32_e32 v108, v82
	v_fma_f32 v82, v93, v224, v113
	v_exp_f32_e32 v109, v82
	v_fma_f32 v82, v94, v224, v113
	v_exp_f32_e32 v110, v82
	v_fma_f32 v82, v95, v224, v113
	v_exp_f32_e32 v111, v82
	v_fma_f32 v82, v96, v224, v113
	v_fma_f32 v113, v97, v224, v113
	s_nop 0
	v_exp_f32_e32 v112, v82

; template <class Epi, class Sched, bool ALIGN_EPI = false, bool SP2 = false>
; __device__ __forceinline__ void gemm_phase(PG8_LAS unsigned char* lds, const Gemm g, const Sched& S, const Epi& E) {
;     ...
;         const char* nA = has_next ? (const char*)g.A + (size_t)nxt.pm * tstepA + (size_t)nxt.kz * kzb : cA; const char* nB = has_next ? (const char*)g.Bt + (size_t)nxt.pn * tstepB + (size_t)nxt.kz * kzb : cB;
;     ...
;         for (int a = 0; a < 2; ++a)
; #pragma unroll
;             for (int b = 0; b < 2; ++b)
; #pragma unroll
;                 for (int m = 0; m < 4; ++m)
; #pragma unroll
;                     for (int n = 0; n < 2; ++n) acc[a][b][m][n] = (f32x4){0.f, 0.f, 0.f, 0.f};
.LBB0_828:
	s_ashr_i32 s19, s18, 31
	s_lshl_b64 s[22:23], s[18:19], 19
	v_readlane_b32 s56, v240, 14
	v_readlane_b32 s57, v240, 15
	s_add_u32 s22, s56, s22
	s_addc_u32 s23, s57, s23
	s_and_b64 s[0:1], s[0:1], exec
	s_cselect_b32 s19, s23, s41
	s_cselect_b32 s55, s22, s40
	s_add_u32 s0, s42, 0x240080
	s_addc_u32 s1, s43, 0
	s_add_u32 s56, s40, 0x100
	v_mov_b64_e32 v[0:1], 0
	s_addc_u32 s57, s41, 0
	s_mov_b32 s58, -2
	v_mov_b64_e32 v[2:3], 0
	v_mov_b64_e32 v[4:5], 0
	v_mov_b64_e32 v[6:7], 0
	v_mov_b64_e32 v[16:17], 0
	v_mov_b64_e32 v[18:19], 0
	v_mov_b64_e32 v[20:21], 0
	v_mov_b64_e32 v[22:23], 0
	v_mov_b64_e32 v[32:33], 0
	v_mov_b64_e32 v[34:35], 0
	v_mov_b64_e32 v[36:37], 0
	v_mov_b64_e32 v[38:39], 0
	v_mov_b64_e32 v[48:49], 0
	v_mov_b64_e32 v[50:51], 0
	v_mov_b64_e32 v[52:53], 0
	v_mov_b64_e32 v[54:55], 0
	v_mov_b64_e32 v[8:9], 0
	v_mov_b64_e32 v[10:11], 0
	v_mov_b64_e32 v[12:13], 0
	v_mov_b64_e32 v[14:15], 0
	v_mov_b64_e32 v[24:25], 0
	v_mov_b64_e32 v[26:27], 0
	v_mov_b64_e32 v[28:29], 0
	v_mov_b64_e32 v[30:31], 0
	v_mov_b64_e32 v[40:41], 0
	v_mov_b64_e32 v[42:43], 0
	v_mov_b64_e32 v[44:45], 0
	v_mov_b64_e32 v[46:47], 0
	v_mov_b64_e32 v[56:57], 0
	v_mov_b64_e32 v[58:59], 0
	v_mov_b64_e32 v[60:61], 0
	v_mov_b64_e32 v[62:63], 0
	v_mov_b64_e32 v[64:65], 0
	v_mov_b64_e32 v[66:67], 0
	v_mov_b64_e32 v[68:69], 0
	v_mov_b64_e32 v[70:71], 0
	v_mov_b64_e32 v[80:81], 0
	v_mov_b64_e32 v[82:83], 0
	v_mov_b64_e32 v[84:85], 0
	v_mov_b64_e32 v[86:87], 0
	v_mov_b64_e32 v[96:97], 0
	v_mov_b64_e32 v[98:99], 0
	v_mov_b64_e32 v[100:101], 0
	v_mov_b64_e32 v[102:103], 0
	v_mov_b64_e32 v[112:113], 0
	v_mov_b64_e32 v[114:115], 0
	v_mov_b64_e32 v[116:117], 0
	v_mov_b64_e32 v[118:119], 0
	v_mov_b64_e32 v[72:73], 0
	v_mov_b64_e32 v[74:75], 0
	v_mov_b64_e32 v[76:77], 0
	v_mov_b64_e32 v[78:79], 0
	v_mov_b64_e32 v[88:89], 0
	v_mov_b64_e32 v[90:91], 0
	v_mov_b64_e32 v[92:93], 0
	v_mov_b64_e32 v[94:95], 0
	v_mov_b64_e32 v[104:105], 0
	v_mov_b64_e32 v[106:107], 0
	v_mov_b64_e32 v[108:109], 0
	v_mov_b64_e32 v[110:111], 0
	v_mov_b64_e32 v[120:121], 0
	v_mov_b64_e32 v[122:123], 0
	v_mov_b64_e32 v[124:125], 0
	v_mov_b64_e32 v[126:127], 0

; template <class Epi, class Sched, bool ALIGN_EPI = false, bool SP2 = false>
; __device__ __forceinline__ void gemm_phase(PG8_LAS unsigned char* lds, const Gemm g, const Sched& S, const Epi& E) {
;     ...
;         const char* nA = has_next ? (const char*)g.A + (size_t)nxt.pm * tstepA + (size_t)nxt.kz * kzb : cA; const char* nB = has_next ? (const char*)g.Bt + (size_t)nxt.pn * tstepB + (size_t)nxt.kz * kzb : cB;
;     ...
;         for (int a = 0; a < 2; ++a)
; #pragma unroll
;             for (int b = 0; b < 2; ++b)
; #pragma unroll
;                 for (int m = 0; m < 4; ++m)
; #pragma unroll
;                     for (int n = 0; n < 2; ++n) acc[a][b][m][n] = (f32x4){0.f, 0.f, 0.f, 0.f};
.LBB0_847:
	s_ashr_i32 s21, s20, 31
	s_lshl_b64 s[30:31], s[20:21], 19
	v_readlane_b32 s40, v240, 12
	v_readlane_b32 s41, v240, 13
	s_add_u32 s40, s40, s30
	s_addc_u32 s41, s41, s31
	s_and_b64 s[0:1], s[0:1], exec
	s_cselect_b32 s21, s41, s43
	s_cselect_b32 s30, s40, s42
	s_add_u32 s0, s44, 0x240080
	s_addc_u32 s1, s45, 0
	s_add_u32 s31, s42, 0x100
	v_mov_b64_e32 v[0:1], 0
	s_addc_u32 s34, s43, 0
	s_mov_b32 s58, -2
	v_mov_b64_e32 v[2:3], 0
	v_mov_b64_e32 v[4:5], 0
	v_mov_b64_e32 v[6:7], 0
	v_mov_b64_e32 v[16:17], 0
	v_mov_b64_e32 v[18:19], 0
	v_mov_b64_e32 v[20:21], 0
	v_mov_b64_e32 v[22:23], 0
	v_mov_b64_e32 v[32:33], 0
	v_mov_b64_e32 v[34:35], 0
	v_mov_b64_e32 v[36:37], 0
	v_mov_b64_e32 v[38:39], 0
	v_mov_b64_e32 v[48:49], 0
	v_mov_b64_e32 v[50:51], 0
	v_mov_b64_e32 v[52:53], 0
	v_mov_b64_e32 v[54:55], 0
	v_mov_b64_e32 v[8:9], 0
	v_mov_b64_e32 v[10:11], 0
	v_mov_b64_e32 v[12:13], 0
	v_mov_b64_e32 v[14:15], 0
	v_mov_b64_e32 v[24:25], 0
	v_mov_b64_e32 v[26:27], 0
	v_mov_b64_e32 v[28:29], 0
	v_mov_b64_e32 v[30:31], 0
	v_mov_b64_e32 v[40:41], 0
	v_mov_b64_e32 v[42:43], 0
	v_mov_b64_e32 v[44:45], 0
	v_mov_b64_e32 v[46:47], 0
	v_mov_b64_e32 v[56:57], 0
	v_mov_b64_e32 v[58:59], 0
	v_mov_b64_e32 v[60:61], 0
	v_mov_b64_e32 v[62:63], 0
	v_mov_b64_e32 v[64:65], 0
	v_mov_b64_e32 v[66:67], 0
	v_mov_b64_e32 v[68:69], 0
	v_mov_b64_e32 v[70:71], 0
	v_mov_b64_e32 v[80:81], 0
	v_mov_b64_e32 v[82:83], 0
	v_mov_b64_e32 v[84:85], 0
	v_mov_b64_e32 v[86:87], 0
	v_mov_b64_e32 v[96:97], 0
	v_mov_b64_e32 v[98:99], 0
	v_mov_b64_e32 v[100:101], 0
	v_mov_b64_e32 v[102:103], 0
	v_mov_b64_e32 v[112:113], 0
	v_mov_b64_e32 v[114:115], 0
	v_mov_b64_e32 v[116:117], 0
	v_mov_b64_e32 v[118:119], 0
	v_mov_b64_e32 v[72:73], 0
	v_mov_b64_e32 v[74:75], 0
	v_mov_b64_e32 v[76:77], 0
	v_mov_b64_e32 v[78:79], 0
	v_mov_b64_e32 v[88:89], 0
	v_mov_b64_e32 v[90:91], 0
	v_mov_b64_e32 v[92:93], 0
	v_mov_b64_e32 v[94:95], 0
	v_mov_b64_e32 v[104:105], 0
	v_mov_b64_e32 v[106:107], 0
	v_mov_b64_e32 v[108:109], 0
	v_mov_b64_e32 v[110:111], 0
	v_mov_b64_e32 v[120:121], 0
	v_mov_b64_e32 v[122:123], 0
	v_mov_b64_e32 v[124:125], 0
	v_mov_b64_e32 v[126:127], 0

; template <class Epi, class Sched, bool ALIGN_EPI = false, bool SP2 = false>
; __device__ __forceinline__ void gemm_phase(PG8_LAS unsigned char* lds, const Gemm g, const Sched& S, const Epi& E) {
;     ...
;         const char* nA = has_next ? (const char*)g.A + (size_t)nxt.pm * tstepA + (size_t)nxt.kz * kzb : cA; const char* nB = has_next ? (const char*)g.Bt + (size_t)nxt.pn * tstepB + (size_t)nxt.kz * kzb : cB;
;     ...
;         for (int a = 0; a < 2; ++a)
; #pragma unroll
;             for (int b = 0; b < 2; ++b)
; #pragma unroll
;                 for (int m = 0; m < 4; ++m)
; #pragma unroll
;                     for (int n = 0; n < 2; ++n) acc[a][b][m][n] = (f32x4){0.f, 0.f, 0.f, 0.f};
.LBB0_926:
	s_ashr_i32 s45, s44, 31
	s_lshl_b64 s[46:47], s[44:45], 20
	v_readlane_b32 s48, v240, 26
	v_readlane_b32 s49, v240, 27
	s_add_u32 s46, s48, s46
	s_addc_u32 s47, s49, s47
	s_and_b64 s[48:49], s[4:5], exec
	s_cselect_b32 s45, s47, s53
	s_cselect_b32 s65, s46, s52
	s_ashr_i32 s43, s42, 31
	s_lshl_b64 s[48:49], s[42:43], 20
	v_readlane_b32 s56, v240, 16
	v_readlane_b32 s57, v240, 17
	s_add_u32 s48, s56, s48
	s_addc_u32 s49, s57, s49
	s_and_b64 s[56:57], s[4:5], exec
	s_cselect_b32 s43, s49, s55
	s_cselect_b32 s68, s48, s54
	s_add_u32 s52, s52, 0x80080
	s_addc_u32 s53, s53, 0
	s_add_u32 s69, s54, 0x100
	v_mov_b64_e32 v[0:1], 0
	s_addc_u32 s70, s55, 0
	s_mov_b32 s71, -2
	v_mov_b64_e32 v[2:3], 0
	v_mov_b64_e32 v[4:5], 0
	v_mov_b64_e32 v[6:7], 0
	v_mov_b64_e32 v[8:9], 0
	v_mov_b64_e32 v[10:11], 0
	v_mov_b64_e32 v[16:17], 0
	v_mov_b64_e32 v[18:19], 0
	v_mov_b64_e32 v[24:25], 0
	v_mov_b64_e32 v[26:27], 0
	v_mov_b64_e32 v[32:33], 0
	v_mov_b64_e32 v[34:35], 0
	v_mov_b64_e32 v[40:41], 0
	v_mov_b64_e32 v[42:43], 0
	v_mov_b64_e32 v[48:49], 0
	v_mov_b64_e32 v[50:51], 0
	v_mov_b64_e32 v[12:13], 0
	v_mov_b64_e32 v[14:15], 0
	v_mov_b64_e32 v[20:21], 0
	v_mov_b64_e32 v[22:23], 0
	v_mov_b64_e32 v[28:29], 0
	v_mov_b64_e32 v[30:31], 0
	v_mov_b64_e32 v[36:37], 0
	v_mov_b64_e32 v[38:39], 0
	v_mov_b64_e32 v[44:45], 0
	v_mov_b64_e32 v[46:47], 0
	v_mov_b64_e32 v[52:53], 0
	v_mov_b64_e32 v[54:55], 0
	v_mov_b64_e32 v[56:57], 0
	v_mov_b64_e32 v[58:59], 0
	v_mov_b64_e32 v[60:61], 0
	v_mov_b64_e32 v[62:63], 0
	v_mov_b64_e32 v[64:65], 0
	v_mov_b64_e32 v[66:67], 0
	v_mov_b64_e32 v[68:69], 0
	v_mov_b64_e32 v[70:71], 0
	v_mov_b64_e32 v[72:73], 0
	v_mov_b64_e32 v[74:75], 0
	v_mov_b64_e32 v[80:81], 0
	v_mov_b64_e32 v[82:83], 0
	v_mov_b64_e32 v[88:89], 0
	v_mov_b64_e32 v[90:91], 0
	v_mov_b64_e32 v[96:97], 0
	v_mov_b64_e32 v[98:99], 0
	v_mov_b64_e32 v[104:105], 0
	v_mov_b64_e32 v[106:107], 0
	v_mov_b64_e32 v[112:113], 0
	v_mov_b64_e32 v[114:115], 0
	v_mov_b64_e32 v[76:77], 0
	v_mov_b64_e32 v[78:79], 0
	v_mov_b64_e32 v[84:85], 0
	v_mov_b64_e32 v[86:87], 0
	v_mov_b64_e32 v[92:93], 0
	v_mov_b64_e32 v[94:95], 0
	v_mov_b64_e32 v[100:101], 0
	v_mov_b64_e32 v[102:103], 0
	v_mov_b64_e32 v[108:109], 0
	v_mov_b64_e32 v[110:111], 0
	v_mov_b64_e32 v[116:117], 0
	v_mov_b64_e32 v[118:119], 0
	v_mov_b64_e32 v[120:121], 0
	v_mov_b64_e32 v[122:123], 0
	v_mov_b64_e32 v[124:125], 0
	v_mov_b64_e32 v[126:127], 0

; template <class Epi, class Sched, bool ALIGN_EPI = false, bool SP2 = false>
; __device__ __forceinline__ void gemm_phase(PG8_LAS unsigned char* lds, const Gemm g, const Sched& S, const Epi& E) {
;     ...
;                 for (int n = 0; n < 2; ++n) acc[a][b][m][n] = (f32x4){0.f, 0.f, 0.f, 0.f};
.LBB0_946:
	v_mov_b64_e32 v[0:1], 0
	s_mov_b32 s19, 0
	s_mov_b64 s[54:55], -1
	s_mov_b64 s[56:57], 0
	v_mov_b64_e32 v[2:3], 0
	v_mov_b64_e32 v[4:5], 0
	v_mov_b64_e32 v[6:7], 0
	v_mov_b64_e32 v[8:9], 0
	v_mov_b64_e32 v[10:11], 0
	v_mov_b64_e32 v[12:13], 0
	v_mov_b64_e32 v[14:15], 0
	v_mov_b64_e32 v[24:25], 0
	v_mov_b64_e32 v[26:27], 0
	v_mov_b64_e32 v[28:29], 0
	v_mov_b64_e32 v[30:31], 0
	v_mov_b64_e32 v[40:41], 0
	v_mov_b64_e32 v[42:43], 0
	v_mov_b64_e32 v[44:45], 0
	v_mov_b64_e32 v[46:47], 0
	v_mov_b64_e32 v[16:17], 0
	v_mov_b64_e32 v[18:19], 0
	v_mov_b64_e32 v[20:21], 0
	v_mov_b64_e32 v[22:23], 0
	v_mov_b64_e32 v[32:33], 0
	v_mov_b64_e32 v[34:35], 0
	v_mov_b64_e32 v[36:37], 0
	v_mov_b64_e32 v[38:39], 0
	v_mov_b64_e32 v[48:49], 0
	v_mov_b64_e32 v[50:51], 0
	v_mov_b64_e32 v[52:53], 0
	v_mov_b64_e32 v[54:55], 0
	v_mov_b64_e32 v[56:57], 0
	v_mov_b64_e32 v[58:59], 0
	v_mov_b64_e32 v[60:61], 0
	v_mov_b64_e32 v[62:63], 0
	v_mov_b64_e32 v[64:65], 0
	v_mov_b64_e32 v[66:67], 0
	v_mov_b64_e32 v[68:69], 0
	v_mov_b64_e32 v[70:71], 0
	v_mov_b64_e32 v[72:73], 0
	v_mov_b64_e32 v[74:75], 0
	v_mov_b64_e32 v[76:77], 0
	v_mov_b64_e32 v[78:79], 0
	v_mov_b64_e32 v[88:89], 0
	v_mov_b64_e32 v[90:91], 0
	v_mov_b64_e32 v[92:93], 0
	v_mov_b64_e32 v[94:95], 0
	v_mov_b64_e32 v[104:105], 0
	v_mov_b64_e32 v[106:107], 0
	v_mov_b64_e32 v[108:109], 0
	v_mov_b64_e32 v[110:111], 0
	v_mov_b64_e32 v[80:81], 0
	v_mov_b64_e32 v[82:83], 0
	v_mov_b64_e32 v[84:85], 0
	v_mov_b64_e32 v[86:87], 0
	v_mov_b64_e32 v[96:97], 0
	v_mov_b64_e32 v[98:99], 0
	v_mov_b64_e32 v[100:101], 0
	v_mov_b64_e32 v[102:103], 0
	v_mov_b64_e32 v[112:113], 0
	v_mov_b64_e32 v[114:115], 0
	v_mov_b64_e32 v[116:117], 0
	v_mov_b64_e32 v[118:119], 0
	v_mov_b64_e32 v[120:121], 0
	v_mov_b64_e32 v[122:123], 0
	v_mov_b64_e32 v[124:125], 0
	v_mov_b64_e32 v[126:127], 0

; template <class Epi, class Sched, bool ALIGN_EPI = false, bool SP2 = false>
; __device__ __forceinline__ void gemm_phase(PG8_LAS unsigned char* lds, const Gemm g, const Sched& S, const Epi& E) {
;     ...
;         const char* nA = has_next ? (const char*)g.A + (size_t)nxt.pm * tstepA + (size_t)nxt.kz * kzb : cA; const char* nB = has_next ? (const char*)g.Bt + (size_t)nxt.pn * tstepB + (size_t)nxt.kz * kzb : cB;
;     ...
;         for (int a = 0; a < 2; ++a)
; #pragma unroll
;             for (int b = 0; b < 2; ++b)
; #pragma unroll
;                 for (int m = 0; m < 4; ++m)
; #pragma unroll
;                     for (int n = 0; n < 2; ++n) acc[a][b][m][n] = (f32x4){0.f, 0.f, 0.f, 0.f};
.LBB0_1081:
	s_ashr_i32 s41, s40, 31
	s_lshl_b64 s[42:43], s[40:41], 20
	s_add_u32 s42, s26, s42
	s_addc_u32 s43, s27, s43
	s_and_b64 s[44:45], s[4:5], exec
	s_cselect_b32 s41, s43, s49
	s_cselect_b32 s62, s42, s48
	s_ashr_i32 s39, s38, 31
	s_lshl_b64 s[44:45], s[38:39], 20
	v_readlane_b32 s52, v240, 18
	v_readlane_b32 s53, v240, 19
	s_add_u32 s44, s52, s44
	s_addc_u32 s45, s53, s45
	s_and_b64 s[52:53], s[4:5], exec
	s_cselect_b32 s39, s45, s51
	s_cselect_b32 s63, s44, s50
	s_add_u32 s48, s48, 0x80080
	s_addc_u32 s49, s49, 0
	s_add_u32 s64, s50, 0x100
	v_mov_b64_e32 v[0:1], 0
	s_addc_u32 s65, s51, 0
	s_mov_b32 s66, -2
	v_mov_b64_e32 v[2:3], 0
	v_mov_b64_e32 v[4:5], 0
	v_mov_b64_e32 v[6:7], 0
	v_mov_b64_e32 v[12:13], 0
	v_mov_b64_e32 v[14:15], 0
	v_mov_b64_e32 v[20:21], 0
	v_mov_b64_e32 v[22:23], 0
	v_mov_b64_e32 v[28:29], 0
	v_mov_b64_e32 v[30:31], 0
	v_mov_b64_e32 v[36:37], 0
	v_mov_b64_e32 v[38:39], 0
	v_mov_b64_e32 v[44:45], 0
	v_mov_b64_e32 v[46:47], 0
	v_mov_b64_e32 v[52:53], 0
	v_mov_b64_e32 v[54:55], 0
	v_mov_b64_e32 v[8:9], 0
	v_mov_b64_e32 v[10:11], 0
	v_mov_b64_e32 v[16:17], 0
	v_mov_b64_e32 v[18:19], 0
	v_mov_b64_e32 v[24:25], 0
	v_mov_b64_e32 v[26:27], 0
	v_mov_b64_e32 v[32:33], 0
	v_mov_b64_e32 v[34:35], 0
	v_mov_b64_e32 v[40:41], 0
	v_mov_b64_e32 v[42:43], 0
	v_mov_b64_e32 v[48:49], 0
	v_mov_b64_e32 v[50:51], 0
	v_mov_b64_e32 v[56:57], 0
	v_mov_b64_e32 v[58:59], 0
	v_mov_b64_e32 v[60:61], 0
	v_mov_b64_e32 v[62:63], 0
	v_mov_b64_e32 v[64:65], 0
	v_mov_b64_e32 v[66:67], 0
	v_mov_b64_e32 v[68:69], 0
	v_mov_b64_e32 v[70:71], 0
	v_mov_b64_e32 v[76:77], 0
	v_mov_b64_e32 v[78:79], 0
	v_mov_b64_e32 v[84:85], 0
	v_mov_b64_e32 v[86:87], 0
	v_mov_b64_e32 v[92:93], 0
	v_mov_b64_e32 v[94:95], 0
	v_mov_b64_e32 v[100:101], 0
	v_mov_b64_e32 v[102:103], 0
	v_mov_b64_e32 v[108:109], 0
	v_mov_b64_e32 v[110:111], 0
	v_mov_b64_e32 v[116:117], 0
	v_mov_b64_e32 v[118:119], 0
	v_mov_b64_e32 v[72:73], 0
	v_mov_b64_e32 v[74:75], 0
	v_mov_b64_e32 v[80:81], 0
	v_mov_b64_e32 v[82:83], 0
	v_mov_b64_e32 v[88:89], 0
	v_mov_b64_e32 v[90:91], 0
	v_mov_b64_e32 v[96:97], 0
	v_mov_b64_e32 v[98:99], 0
	v_mov_b64_e32 v[104:105], 0
	v_mov_b64_e32 v[106:107], 0
	v_mov_b64_e32 v[112:113], 0
	v_mov_b64_e32 v[114:115], 0
	v_mov_b64_e32 v[120:121], 0
	v_mov_b64_e32 v[122:123], 0
	v_mov_b64_e32 v[124:125], 0
	v_mov_b64_e32 v[126:127], 0

; template <class Epi, class Sched, bool ALIGN_EPI = false, bool SP2 = false>
; __device__ __forceinline__ void gemm_phase(PG8_LAS unsigned char* lds, const Gemm g, const Sched& S, const Epi& E) {
;     ...
;         const char* nA = has_next ? (const char*)g.A + (size_t)nxt.pm * tstepA + (size_t)nxt.kz * kzb : cA; const char* nB = has_next ? (const char*)g.Bt + (size_t)nxt.pn * tstepB + (size_t)nxt.kz * kzb : cB;
;     ...
;         for (int a = 0; a < 2; ++a)
; #pragma unroll
;             for (int b = 0; b < 2; ++b)
; #pragma unroll
;                 for (int m = 0; m < 4; ++m)
; #pragma unroll
;                     for (int n = 0; n < 2; ++n) acc[a][b][m][n] = (f32x4){0.f, 0.f, 0.f, 0.f};
.LBB0_1160:
	s_ashr_i32 s41, s40, 31
	s_lshl_b64 s[42:43], s[40:41], 22
	s_add_u32 s42, s12, s42
	s_addc_u32 s43, s13, s43
	s_and_b64 s[44:45], s[4:5], exec
	s_cselect_b32 s41, s43, s49
	s_cselect_b32 s61, s42, s48
	s_ashr_i32 s39, s38, 31
	s_lshl_b64 s[44:45], s[38:39], 22
	v_readlane_b32 s52, v240, 20
	v_readlane_b32 s53, v240, 21
	s_add_u32 s44, s52, s44
	s_addc_u32 s45, s53, s45
	s_and_b64 s[52:53], s[4:5], exec
	s_cselect_b32 s39, s45, s51
	s_cselect_b32 s62, s44, s50
	s_add_u32 s48, s48, 0x200080
	s_addc_u32 s49, s49, 0
	s_add_u32 s63, s50, 0x100
	v_mov_b64_e32 v[0:1], 0
	s_addc_u32 s64, s51, 0
	s_mov_b32 s65, -2
	v_mov_b64_e32 v[2:3], 0
	v_mov_b64_e32 v[4:5], 0
	v_mov_b64_e32 v[6:7], 0
	v_mov_b64_e32 v[8:9], 0
	v_mov_b64_e32 v[10:11], 0
	v_mov_b64_e32 v[16:17], 0
	v_mov_b64_e32 v[18:19], 0
	v_mov_b64_e32 v[24:25], 0
	v_mov_b64_e32 v[26:27], 0
	v_mov_b64_e32 v[32:33], 0
	v_mov_b64_e32 v[34:35], 0
	v_mov_b64_e32 v[40:41], 0
	v_mov_b64_e32 v[42:43], 0
	v_mov_b64_e32 v[48:49], 0
	v_mov_b64_e32 v[50:51], 0
	v_mov_b64_e32 v[12:13], 0
	v_mov_b64_e32 v[14:15], 0
	v_mov_b64_e32 v[20:21], 0
	v_mov_b64_e32 v[22:23], 0
	v_mov_b64_e32 v[28:29], 0
	v_mov_b64_e32 v[30:31], 0
	v_mov_b64_e32 v[36:37], 0
	v_mov_b64_e32 v[38:39], 0
	v_mov_b64_e32 v[44:45], 0
	v_mov_b64_e32 v[46:47], 0
	v_mov_b64_e32 v[52:53], 0
	v_mov_b64_e32 v[54:55], 0
	v_mov_b64_e32 v[56:57], 0
	v_mov_b64_e32 v[58:59], 0
	v_mov_b64_e32 v[60:61], 0
	v_mov_b64_e32 v[62:63], 0
	v_mov_b64_e32 v[64:65], 0
	v_mov_b64_e32 v[66:67], 0
	v_mov_b64_e32 v[68:69], 0
	v_mov_b64_e32 v[70:71], 0
	v_mov_b64_e32 v[76:77], 0
	v_mov_b64_e32 v[78:79], 0
	v_mov_b64_e32 v[84:85], 0
	v_mov_b64_e32 v[86:87], 0
	v_mov_b64_e32 v[88:89], 0
	v_mov_b64_e32 v[90:91], 0
	v_mov_b64_e32 v[96:97], 0
	v_mov_b64_e32 v[98:99], 0
	v_mov_b64_e32 v[104:105], 0
	v_mov_b64_e32 v[106:107], 0
	v_mov_b64_e32 v[112:113], 0
	v_mov_b64_e32 v[114:115], 0
	v_mov_b64_e32 v[72:73], 0
	v_mov_b64_e32 v[74:75], 0
	v_mov_b64_e32 v[80:81], 0
	v_mov_b64_e32 v[82:83], 0
	v_mov_b64_e32 v[92:93], 0
	v_mov_b64_e32 v[94:95], 0
	v_mov_b64_e32 v[100:101], 0
	v_mov_b64_e32 v[102:103], 0
	v_mov_b64_e32 v[108:109], 0
	v_mov_b64_e32 v[110:111], 0
	v_mov_b64_e32 v[116:117], 0
	v_mov_b64_e32 v[118:119], 0
	v_mov_b64_e32 v[120:121], 0
	v_mov_b64_e32 v[122:123], 0
	v_mov_b64_e32 v[124:125], 0
	v_mov_b64_e32 v[126:127], 0

; template <class Epi, class Sched, bool ALIGN_EPI = false, bool SP2 = false>
; __device__ __forceinline__ void gemm_phase(PG8_LAS unsigned char* lds, const Gemm g, const Sched& S, const Epi& E) {
;     ...
;         for (int a = 0; a < 2; ++a)
; #pragma unroll
;             for (int b = 0; b < 2; ++b)
; #pragma unroll
;                 for (int m = 0; m < 4; ++m)
; #pragma unroll
;                     for (int n = 0; n < 2; ++n) acc[a][b][m][n] = (f32x4){0.f, 0.f, 0.f, 0.f};
.LBB0_1180:
	s_add_u32 s46, s46, 0x200080
	s_addc_u32 s47, s47, 0
	s_add_u32 s19, s48, 0x100
	v_mov_b64_e32 v[0:1], 0
	s_addc_u32 s39, s49, 0
	s_mov_b32 s41, -2
	v_mov_b64_e32 v[2:3], 0
	v_mov_b64_e32 v[4:5], 0
	v_mov_b64_e32 v[6:7], 0
	v_mov_b64_e32 v[8:9], 0
	v_mov_b64_e32 v[10:11], 0
	v_mov_b64_e32 v[12:13], 0
	v_mov_b64_e32 v[14:15], 0
	v_mov_b64_e32 v[24:25], 0
	v_mov_b64_e32 v[26:27], 0
	v_mov_b64_e32 v[28:29], 0
	v_mov_b64_e32 v[30:31], 0
	v_mov_b64_e32 v[40:41], 0
	v_mov_b64_e32 v[42:43], 0
	v_mov_b64_e32 v[44:45], 0
	v_mov_b64_e32 v[46:47], 0
	v_mov_b64_e32 v[16:17], 0
	v_mov_b64_e32 v[18:19], 0
	v_mov_b64_e32 v[20:21], 0
	v_mov_b64_e32 v[22:23], 0
	v_mov_b64_e32 v[32:33], 0
	v_mov_b64_e32 v[34:35], 0
	v_mov_b64_e32 v[36:37], 0
	v_mov_b64_e32 v[38:39], 0
	v_mov_b64_e32 v[48:49], 0
	v_mov_b64_e32 v[50:51], 0
	v_mov_b64_e32 v[52:53], 0
	v_mov_b64_e32 v[54:55], 0
	v_mov_b64_e32 v[56:57], 0
	v_mov_b64_e32 v[58:59], 0
	v_mov_b64_e32 v[60:61], 0
	v_mov_b64_e32 v[62:63], 0
	v_mov_b64_e32 v[64:65], 0
	v_mov_b64_e32 v[66:67], 0
	v_mov_b64_e32 v[68:69], 0
	v_mov_b64_e32 v[70:71], 0
	v_mov_b64_e32 v[72:73], 0
	v_mov_b64_e32 v[74:75], 0
	v_mov_b64_e32 v[76:77], 0
	v_mov_b64_e32 v[78:79], 0
	v_mov_b64_e32 v[88:89], 0
	v_mov_b64_e32 v[90:91], 0
	v_mov_b64_e32 v[92:93], 0
	v_mov_b64_e32 v[94:95], 0
	v_mov_b64_e32 v[104:105], 0
	v_mov_b64_e32 v[106:107], 0
	v_mov_b64_e32 v[108:109], 0
	v_mov_b64_e32 v[110:111], 0
	v_mov_b64_e32 v[80:81], 0
	v_mov_b64_e32 v[82:83], 0
	v_mov_b64_e32 v[84:85], 0
	v_mov_b64_e32 v[86:87], 0
	v_mov_b64_e32 v[96:97], 0
	v_mov_b64_e32 v[98:99], 0
	v_mov_b64_e32 v[100:101], 0
	v_mov_b64_e32 v[102:103], 0
	v_mov_b64_e32 v[112:113], 0
	v_mov_b64_e32 v[114:115], 0
	v_mov_b64_e32 v[116:117], 0
	v_mov_b64_e32 v[118:119], 0
	v_mov_b64_e32 v[120:121], 0
	v_mov_b64_e32 v[122:123], 0
	v_mov_b64_e32 v[124:125], 0
	v_mov_b64_e32 v[126:127], 0

; template <class Epi, class Sched, bool ALIGN_EPI = false, bool SP2 = false>
; __device__ __forceinline__ void gemm_phase(PG8_LAS unsigned char* lds, const Gemm g, const Sched& S, const Epi& E) {
;     ...
;         const char* nA = has_next ? (const char*)g.A + (size_t)nxt.pm * tstepA + (size_t)nxt.kz * kzb : cA; const char* nB = has_next ? (const char*)g.Bt + (size_t)nxt.pn * tstepB + (size_t)nxt.kz * kzb : cB;
;     ...
;         for (int a = 0; a < 2; ++a)
; #pragma unroll
;             for (int b = 0; b < 2; ++b)
; #pragma unroll
;                 for (int m = 0; m < 4; ++m)
; #pragma unroll
;                     for (int n = 0; n < 2; ++n) acc[a][b][m][n] = (f32x4){0.f, 0.f, 0.f, 0.f};
.LBB0_1261:
	s_ashr_i32 s23, s22, 31
	s_lshl_b64 s[36:37], s[22:23], 17
	s_add_u32 s36, s29, s36
	s_addc_u32 s37, s30, s37
	s_and_b64 s[38:39], s[4:5], exec
	s_cselect_b32 s23, s37, s45
	s_cselect_b32 s69, s36, s44
	s_ashr_i32 s21, s20, 31
	s_lshl_b64 s[38:39], s[20:21], 17
	v_readlane_b32 s46, v240, 22
	v_readlane_b32 s47, v240, 23
	s_add_u32 s38, s46, s38
	s_addc_u32 s39, s47, s39
	s_and_b64 s[46:47], s[4:5], exec
	v_mov_b64_e32 v[0:1], 0
	s_cselect_b32 s21, s39, s43
	s_cselect_b32 s70, s38, s42
	s_mov_b32 s50, 0
	s_mov_b64 s[46:47], -1
	s_mov_b64 s[48:49], 0
	v_mov_b64_e32 v[2:3], 0
	v_mov_b64_e32 v[4:5], 0
	v_mov_b64_e32 v[6:7], 0
	v_mov_b64_e32 v[8:9], 0
	v_mov_b64_e32 v[10:11], 0
	v_mov_b64_e32 v[16:17], 0
	v_mov_b64_e32 v[18:19], 0
	v_mov_b64_e32 v[24:25], 0
	v_mov_b64_e32 v[26:27], 0
	v_mov_b64_e32 v[32:33], 0
	v_mov_b64_e32 v[34:35], 0
	v_mov_b64_e32 v[40:41], 0
	v_mov_b64_e32 v[42:43], 0
	v_mov_b64_e32 v[48:49], 0
	v_mov_b64_e32 v[50:51], 0
	v_mov_b64_e32 v[12:13], 0
	v_mov_b64_e32 v[14:15], 0
	v_mov_b64_e32 v[20:21], 0
	v_mov_b64_e32 v[22:23], 0
	v_mov_b64_e32 v[28:29], 0
	v_mov_b64_e32 v[30:31], 0
	v_mov_b64_e32 v[36:37], 0
	v_mov_b64_e32 v[38:39], 0
	v_mov_b64_e32 v[44:45], 0
	v_mov_b64_e32 v[46:47], 0
	v_mov_b64_e32 v[52:53], 0
	v_mov_b64_e32 v[54:55], 0
	v_mov_b64_e32 v[56:57], 0
	v_mov_b64_e32 v[58:59], 0
	v_mov_b64_e32 v[60:61], 0
	v_mov_b64_e32 v[62:63], 0
	v_mov_b64_e32 v[64:65], 0
	v_mov_b64_e32 v[66:67], 0
	v_mov_b64_e32 v[68:69], 0
	v_mov_b64_e32 v[70:71], 0
	v_mov_b64_e32 v[72:73], 0
	v_mov_b64_e32 v[74:75], 0
	v_mov_b64_e32 v[80:81], 0
	v_mov_b64_e32 v[82:83], 0
	v_mov_b64_e32 v[88:89], 0
	v_mov_b64_e32 v[90:91], 0
	v_mov_b64_e32 v[96:97], 0
	v_mov_b64_e32 v[98:99], 0
	v_mov_b64_e32 v[104:105], 0
	v_mov_b64_e32 v[106:107], 0
	v_mov_b64_e32 v[112:113], 0
	v_mov_b64_e32 v[114:115], 0
	v_mov_b64_e32 v[76:77], 0
	v_mov_b64_e32 v[78:79], 0
	v_mov_b64_e32 v[84:85], 0
	v_mov_b64_e32 v[86:87], 0
	v_mov_b64_e32 v[92:93], 0
	v_mov_b64_e32 v[94:95], 0
	v_mov_b64_e32 v[100:101], 0
	v_mov_b64_e32 v[102:103], 0
	v_mov_b64_e32 v[108:109], 0
	v_mov_b64_e32 v[110:111], 0
	v_mov_b64_e32 v[116:117], 0
	v_mov_b64_e32 v[118:119], 0
	v_mov_b64_e32 v[120:121], 0
	v_mov_b64_e32 v[122:123], 0
	v_mov_b64_e32 v[124:125], 0
	v_mov_b64_e32 v[126:127], 0

; template <class Epi, class Sched, bool ALIGN_EPI = false, bool SP2 = false>
; __device__ __forceinline__ void gemm_phase(PG8_LAS unsigned char* lds, const Gemm g, const Sched& S, const Epi& E) {
;     ...
;         const char* nA = has_next ? (const char*)g.A + (size_t)nxt.pm * tstepA + (size_t)nxt.kz * kzb : cA; const char* nB = has_next ? (const char*)g.Bt + (size_t)nxt.pn * tstepB + (size_t)nxt.kz * kzb : cB;
;     ...
;         for (int a = 0; a < 2; ++a)
; #pragma unroll
;             for (int b = 0; b < 2; ++b)
; #pragma unroll
;                 for (int m = 0; m < 4; ++m)
; #pragma unroll
;                     for (int n = 0; n < 2; ++n) acc[a][b][m][n] = (f32x4){0.f, 0.f, 0.f, 0.f};
.LBB0_1332:
	s_ashr_i32 s37, s36, 31
	s_lshl_b64 s[38:39], s[36:37], 20
	v_readlane_b32 s40, v240, 26
	v_readlane_b32 s41, v240, 27
	s_add_u32 s38, s40, s38
	s_addc_u32 s39, s41, s39
	s_and_b64 s[40:41], s[4:5], exec
	s_cselect_b32 s37, s39, s45
	s_cselect_b32 s58, s38, s44
	s_ashr_i32 s23, s22, 31
	s_lshl_b64 s[40:41], s[22:23], 20
	v_readlane_b32 s48, v240, 24
	v_readlane_b32 s49, v240, 25
	s_add_u32 s40, s48, s40
	s_addc_u32 s41, s49, s41
	s_and_b64 s[48:49], s[4:5], exec
	s_cselect_b32 s23, s41, s47
	s_cselect_b32 s59, s40, s46
	s_add_u32 s44, s44, 0x80080
	s_addc_u32 s45, s45, 0
	s_add_u32 s60, s46, 0x100
	v_mov_b64_e32 v[0:1], 0
	s_addc_u32 s61, s47, 0
	s_mov_b32 s62, -2
	v_mov_b64_e32 v[2:3], 0
	v_mov_b64_e32 v[4:5], 0
	v_mov_b64_e32 v[6:7], 0
	v_mov_b64_e32 v[16:17], 0
	v_mov_b64_e32 v[18:19], 0
	v_mov_b64_e32 v[20:21], 0
	v_mov_b64_e32 v[22:23], 0
	v_mov_b64_e32 v[32:33], 0
	v_mov_b64_e32 v[34:35], 0
	v_mov_b64_e32 v[36:37], 0
	v_mov_b64_e32 v[38:39], 0
	v_mov_b64_e32 v[48:49], 0
	v_mov_b64_e32 v[50:51], 0
	v_mov_b64_e32 v[52:53], 0
	v_mov_b64_e32 v[54:55], 0
	v_mov_b64_e32 v[8:9], 0
	v_mov_b64_e32 v[10:11], 0
	v_mov_b64_e32 v[12:13], 0
	v_mov_b64_e32 v[14:15], 0
	v_mov_b64_e32 v[24:25], 0
	v_mov_b64_e32 v[26:27], 0
	v_mov_b64_e32 v[28:29], 0
	v_mov_b64_e32 v[30:31], 0
	v_mov_b64_e32 v[40:41], 0
	v_mov_b64_e32 v[42:43], 0
	v_mov_b64_e32 v[44:45], 0
	v_mov_b64_e32 v[46:47], 0
	v_mov_b64_e32 v[56:57], 0
	v_mov_b64_e32 v[58:59], 0
	v_mov_b64_e32 v[60:61], 0
	v_mov_b64_e32 v[62:63], 0
	v_mov_b64_e32 v[64:65], 0
	v_mov_b64_e32 v[66:67], 0
	v_mov_b64_e32 v[68:69], 0
	v_mov_b64_e32 v[70:71], 0
	v_mov_b64_e32 v[80:81], 0
	v_mov_b64_e32 v[82:83], 0
	v_mov_b64_e32 v[84:85], 0
	v_mov_b64_e32 v[86:87], 0
	v_mov_b64_e32 v[96:97], 0
	v_mov_b64_e32 v[98:99], 0
	v_mov_b64_e32 v[100:101], 0
	v_mov_b64_e32 v[102:103], 0
	v_mov_b64_e32 v[112:113], 0
	v_mov_b64_e32 v[114:115], 0
	v_mov_b64_e32 v[116:117], 0
	v_mov_b64_e32 v[118:119], 0
	v_mov_b64_e32 v[72:73], 0
	v_mov_b64_e32 v[74:75], 0
	v_mov_b64_e32 v[76:77], 0
	v_mov_b64_e32 v[78:79], 0
	v_mov_b64_e32 v[88:89], 0
	v_mov_b64_e32 v[90:91], 0
	v_mov_b64_e32 v[92:93], 0
	v_mov_b64_e32 v[94:95], 0
	v_mov_b64_e32 v[104:105], 0
	v_mov_b64_e32 v[106:107], 0
	v_mov_b64_e32 v[108:109], 0
	v_mov_b64_e32 v[110:111], 0
	v_mov_b64_e32 v[120:121], 0
	v_mov_b64_e32 v[122:123], 0
	v_mov_b64_e32 v[124:125], 0
	v_mov_b64_e32 v[126:127], 0
